# P2 x_m^T tiles: token pairs packed via DPP swap, dword stores instead of 2-byte stores
# baseline (speedup 1.0000x reference)
; DI unsigned short f2bf(float x) { return (unsigned short)(pk2(x, 0.f) & 0xffffu); }
; DI uint4 pk8(f32x4 a, f32x4 b) { return make_uint4(pk2(a[0], a[1]), pk2(a[2], a[3]), pk2(b[0], b[1]), pk2(b[2], b[3])); }
;     DI void operator()(const f32x4 (&acc)[2][2][4][2], const pg8::Unit& u, int wr, int wc, int fr, int fq) const {
;     ...
;         if (pn < 4) {
; #pragma unroll
;             for (int i = 0; i < 16; ++i) {
;                 const int ai = TILE_AI(i), m = TILE_M(i), bj = TILE_BJ(i);
;                 const int t = t0 + ai * 128 + m * 16, col = colb + bj * 128;
;                 const f32x4 v0 = acc[ai][bj][m][0] + bia[bj][0], v1 = acc[ai][bj][m][1] + bia[bj][1];
;                 *(uint4*)(xm + (size_t)t * 1024 + col) = pk8(v0, v1);
;                 const int b = t >> 13, sidx = t & 8191;
;                 bf16_t* tp = xmT + ((((size_t)(b * 4 + (col >> 8)) * 128 + (sidx >> 6)) * 256 + (col & 255)) * 64) + (sidx & 63);
; #pragma unroll
;                 for (int r = 0; r < 4; ++r) { *tp = f2bf(v0[r]); tp += 64; asm volatile("" : "+v"(tp)); }
; #pragma unroll
;                 for (int r = 0; r < 4; ++r) { *tp = f2bf(v1[r]); tp += 64; asm volatile("" : "+v"(tp)); }
;             }
.LBB0_301:
	v_and_b32_e32 v252, 1, v176
	v_mov_b32_e32 v253, 0
	s_mov_b64 s[98:99], 0x100
	v_cmp_eq_u32_e64 s[96:97], 1, v252
	v_mul_u32_u24_e32 v252, 0x7e, v252
	v_ashrrev_i32_e32 v163, 31, v162
	v_readlane_b32 s18, v254, 56
	v_lshlrev_b64 v[166:167], 11, v[162:163]
	v_readlane_b32 s19, v254, 57
	v_cvt_pk_bf16_f32 v178, v140, v141
	v_cvt_pk_bf16_f32 v179, v142, v143
	v_lshl_add_u64 v[168:169], s[18:19], 0, v[166:167]
	v_lshlrev_b64 v[166:167], 1, v[164:165]
	v_cvt_pk_bf16_f32 v180, v136, v137
	v_cvt_pk_bf16_f32 v181, v138, v139
	v_lshl_add_u64 v[168:169], v[168:169], 0, v[166:167]
	v_ashrrev_i32_e32 v152, 11, v162
	global_store_dwordx4 v[168:169], v[178:181], off
	s_nop 0
	v_ashrrev_i32_e32 v163, 8, v164
	v_and_b32_e32 v165, 0xf8, v177
	v_and_b32_e32 v180, -4, v152
	v_add_u32_e32 v178, v163, v180
	v_ashrrev_i32_e32 v179, 31, v178
	v_lshlrev_b32_e32 v152, 2, v162
	v_lshlrev_b64 v[178:179], 15, v[178:179]
	v_and_b32_e32 v181, 0x7f00, v152
	v_or3_b32 v178, v178, v181, v165
	v_lshlrev_b64 v[178:179], 7, v[178:179]
	v_and_b32_e32 v152, 63, v176
	v_lshl_add_u64 v[178:179], s[92:93], 0, v[178:179]
	v_lshlrev_b32_e32 v152, 1, v152
	v_lshl_add_u64 v[176:177], v[178:179], 0, v[152:153]
	v_lshl_add_u64 v[224:225], v[176:177], 0, v[252:253]
	s_nop 0
	v_mov_b32_dpp v245, v140 quad_perm:[1,0,3,2] row_mask:0xf bank_mask:0xf
	v_mov_b32_dpp v246, v141 quad_perm:[1,0,3,2] row_mask:0xf bank_mask:0xf
	v_cndmask_b32_e64 v247, v140, v246, s[96:97]
	v_cndmask_b32_e64 v248, v245, v141, s[96:97]
	v_cvt_pk_bf16_f32 v247, v247, v248
	global_store_dword v[224:225], v247, off
	v_lshl_add_u64 v[224:225], v[224:225], 0, s[98:99]
	v_mov_b32_dpp v245, v142 quad_perm:[1,0,3,2] row_mask:0xf bank_mask:0xf
	v_mov_b32_dpp v246, v143 quad_perm:[1,0,3,2] row_mask:0xf bank_mask:0xf
	v_cndmask_b32_e64 v247, v142, v246, s[96:97]
	v_cndmask_b32_e64 v248, v245, v143, s[96:97]
	v_cvt_pk_bf16_f32 v247, v247, v248
	global_store_dword v[224:225], v247, off
	v_lshl_add_u64 v[224:225], v[224:225], 0, s[98:99]
	v_mov_b32_dpp v245, v136 quad_perm:[1,0,3,2] row_mask:0xf bank_mask:0xf
	v_mov_b32_dpp v246, v137 quad_perm:[1,0,3,2] row_mask:0xf bank_mask:0xf
	v_cndmask_b32_e64 v247, v136, v246, s[96:97]
	v_cndmask_b32_e64 v248, v245, v137, s[96:97]
	v_cvt_pk_bf16_f32 v247, v247, v248
	global_store_dword v[224:225], v247, off
	v_lshl_add_u64 v[224:225], v[224:225], 0, s[98:99]
	v_mov_b32_dpp v245, v138 quad_perm:[1,0,3,2] row_mask:0xf bank_mask:0xf
	v_mov_b32_dpp v246, v139 quad_perm:[1,0,3,2] row_mask:0xf bank_mask:0xf
	v_cndmask_b32_e64 v247, v138, v246, s[96:97]
	v_cndmask_b32_e64 v248, v245, v139, s[96:97]
	v_cvt_pk_bf16_f32 v247, v247, v248
	global_store_dword v[224:225], v247, off
	v_pk_add_f32 v[134:135], v[134:135], v[98:99]
	v_pk_add_f32 v[132:133], v[132:133], v[96:97]
	v_pk_add_f32 v[136:137], v[130:131], v[94:95]
	v_pk_add_f32 v[138:139], v[128:129], v[92:93]
	v_add_u32_e32 v140, 0x80, v164
	v_cvt_pk_bf16_f32 v128, v132, v133
	v_cvt_pk_bf16_f32 v129, v134, v135
	v_cvt_pk_bf16_f32 v130, v138, v139
	v_cvt_pk_bf16_f32 v131, v136, v137
	global_store_dwordx4 v[168:169], v[128:131], off offset:256
	s_nop 0
	v_pk_add_f32 v[126:127], v[126:127], v[118:119]
	v_ashrrev_i32_e32 v128, 8, v140
	v_add_u32_e32 v130, v128, v180
	v_ashrrev_i32_e32 v131, 31, v130
	v_lshlrev_b64 v[130:131], 15, v[130:131]
	v_and_b32_e32 v129, 0xf8, v140
	v_or3_b32 v130, v130, v181, v129
	v_lshlrev_b64 v[130:131], 7, v[130:131]
	v_lshl_add_u64 v[130:131], s[92:93], 0, v[130:131]
	v_lshl_add_u64 v[130:131], v[130:131], 0, v[152:153]
	v_lshl_add_u64 v[224:225], v[130:131], 0, v[252:253]
	s_nop 0
	v_mov_b32_dpp v245, v132 quad_perm:[1,0,3,2] row_mask:0xf bank_mask:0xf
	v_mov_b32_dpp v246, v133 quad_perm:[1,0,3,2] row_mask:0xf bank_mask:0xf
	v_cndmask_b32_e64 v247, v132, v246, s[96:97]
	v_cndmask_b32_e64 v248, v245, v133, s[96:97]
	v_cvt_pk_bf16_f32 v247, v247, v248
	global_store_dword v[224:225], v247, off
	v_lshl_add_u64 v[224:225], v[224:225], 0, s[98:99]
	v_mov_b32_dpp v245, v134 quad_perm:[1,0,3,2] row_mask:0xf bank_mask:0xf
	v_mov_b32_dpp v246, v135 quad_perm:[1,0,3,2] row_mask:0xf bank_mask:0xf
	v_cndmask_b32_e64 v247, v134, v246, s[96:97]
	v_cndmask_b32_e64 v248, v245, v135, s[96:97]
	v_cvt_pk_bf16_f32 v247, v247, v248
	global_store_dword v[224:225], v247, off
	v_lshl_add_u64 v[224:225], v[224:225], 0, s[98:99]
	v_mov_b32_dpp v245, v138 quad_perm:[1,0,3,2] row_mask:0xf bank_mask:0xf
	v_mov_b32_dpp v246, v139 quad_perm:[1,0,3,2] row_mask:0xf bank_mask:0xf
	v_cndmask_b32_e64 v247, v138, v246, s[96:97]
	v_cndmask_b32_e64 v248, v245, v139, s[96:97]
	v_cvt_pk_bf16_f32 v247, v247, v248
	global_store_dword v[224:225], v247, off
	v_lshl_add_u64 v[224:225], v[224:225], 0, s[98:99]
	v_mov_b32_dpp v245, v136 quad_perm:[1,0,3,2] row_mask:0xf bank_mask:0xf
	v_mov_b32_dpp v246, v137 quad_perm:[1,0,3,2] row_mask:0xf bank_mask:0xf
	v_cndmask_b32_e64 v247, v136, v246, s[96:97]
	v_cndmask_b32_e64 v248, v245, v137, s[96:97]
	v_cvt_pk_bf16_f32 v247, v247, v248
	global_store_dword v[224:225], v247, off
	v_pk_add_f32 v[124:125], v[124:125], v[116:117]
	v_add_u32_e32 v130, 16, v162
	v_ashrrev_i32_e32 v131, 31, v130
	v_lshlrev_b64 v[136:137], 11, v[130:131]
	v_pk_add_f32 v[132:133], v[122:123], v[114:115]
	v_pk_add_f32 v[134:135], v[120:121], v[112:113]
	v_lshl_add_u64 v[136:137], s[18:19], 0, v[136:137]
	v_cvt_pk_bf16_f32 v120, v124, v125
	v_cvt_pk_bf16_f32 v121, v126, v127
	v_cvt_pk_bf16_f32 v122, v134, v135
	v_cvt_pk_bf16_f32 v123, v132, v133
	v_lshl_add_u64 v[136:137], v[136:137], 0, v[166:167]
	global_store_dwordx4 v[136:137], v[120:123], off
	s_nop 0
	v_pk_add_f32 v[110:111], v[110:111], v[98:99]
	v_ashrrev_i32_e32 v120, 11, v130
; DI unsigned short f2bf(float x) { return (unsigned short)(pk2(x, 0.f) & 0xffffu); }
; DI uint4 pk8(f32x4 a, f32x4 b) { return make_uint4(pk2(a[0], a[1]), pk2(a[2], a[3]), pk2(b[0], b[1]), pk2(b[2], b[3])); }
;     DI void operator()(const f32x4 (&acc)[2][2][4][2], const pg8::Unit& u, int wr, int wc, int fr, int fq) const {
;     ...
;         if (pn < 4) {
; #pragma unroll
;             for (int i = 0; i < 16; ++i) {
;                 const int ai = TILE_AI(i), m = TILE_M(i), bj = TILE_BJ(i);
;                 const int t = t0 + ai * 128 + m * 16, col = colb + bj * 128;
;                 const f32x4 v0 = acc[ai][bj][m][0] + bia[bj][0], v1 = acc[ai][bj][m][1] + bia[bj][1];
;                 *(uint4*)(xm + (size_t)t * 1024 + col) = pk8(v0, v1);
;                 const int b = t >> 13, sidx = t & 8191;
;                 bf16_t* tp = xmT + ((((size_t)(b * 4 + (col >> 8)) * 128 + (sidx >> 6)) * 256 + (col & 255)) * 64) + (sidx & 63);
; #pragma unroll
;                 for (int r = 0; r < 4; ++r) { *tp = f2bf(v0[r]); tp += 64; asm volatile("" : "+v"(tp)); }
; #pragma unroll
;                 for (int r = 0; r < 4; ++r) { *tp = f2bf(v1[r]); tp += 64; asm volatile("" : "+v"(tp)); }
;             }
	v_and_b32_e32 v131, -4, v120
	v_add_u32_e32 v120, v163, v131
	v_ashrrev_i32_e32 v121, 31, v120
	v_lshlrev_b32_e32 v122, 2, v130
	v_lshlrev_b64 v[120:121], 15, v[120:121]
	v_and_b32_e32 v138, 0x7f00, v122
	v_or3_b32 v120, v120, v138, v165
	v_lshlrev_b64 v[120:121], 7, v[120:121]
	v_and_b32_e32 v122, 63, v130
	v_lshl_add_u64 v[120:121], s[92:93], 0, v[120:121]
	v_lshlrev_b32_e32 v122, 1, v122
	v_mov_b32_e32 v123, v153
	v_lshl_add_u64 v[120:121], v[120:121], 0, v[122:123]
	v_lshl_add_u64 v[224:225], v[120:121], 0, v[252:253]
	s_nop 0
	v_mov_b32_dpp v245, v124 quad_perm:[1,0,3,2] row_mask:0xf bank_mask:0xf
	v_mov_b32_dpp v246, v125 quad_perm:[1,0,3,2] row_mask:0xf bank_mask:0xf
	v_cndmask_b32_e64 v247, v124, v246, s[96:97]
	v_cndmask_b32_e64 v248, v245, v125, s[96:97]
	v_cvt_pk_bf16_f32 v247, v247, v248
	global_store_dword v[224:225], v247, off
	v_lshl_add_u64 v[224:225], v[224:225], 0, s[98:99]
	v_mov_b32_dpp v245, v126 quad_perm:[1,0,3,2] row_mask:0xf bank_mask:0xf
	v_mov_b32_dpp v246, v127 quad_perm:[1,0,3,2] row_mask:0xf bank_mask:0xf
	v_cndmask_b32_e64 v247, v126, v246, s[96:97]
	v_cndmask_b32_e64 v248, v245, v127, s[96:97]
	v_cvt_pk_bf16_f32 v247, v247, v248
	global_store_dword v[224:225], v247, off
	v_lshl_add_u64 v[224:225], v[224:225], 0, s[98:99]
	v_mov_b32_dpp v245, v134 quad_perm:[1,0,3,2] row_mask:0xf bank_mask:0xf
	v_mov_b32_dpp v246, v135 quad_perm:[1,0,3,2] row_mask:0xf bank_mask:0xf
	v_cndmask_b32_e64 v247, v134, v246, s[96:97]
	v_cndmask_b32_e64 v248, v245, v135, s[96:97]
	v_cvt_pk_bf16_f32 v247, v247, v248
	global_store_dword v[224:225], v247, off
	v_lshl_add_u64 v[224:225], v[224:225], 0, s[98:99]
	v_mov_b32_dpp v245, v132 quad_perm:[1,0,3,2] row_mask:0xf bank_mask:0xf
	v_mov_b32_dpp v246, v133 quad_perm:[1,0,3,2] row_mask:0xf bank_mask:0xf
	v_cndmask_b32_e64 v247, v132, v246, s[96:97]
	v_cndmask_b32_e64 v248, v245, v133, s[96:97]
	v_cvt_pk_bf16_f32 v247, v247, v248
	global_store_dword v[224:225], v247, off
	v_pk_add_f32 v[108:109], v[108:109], v[96:97]
	v_pk_add_f32 v[120:121], v[106:107], v[94:95]
	v_pk_add_f32 v[124:125], v[104:105], v[92:93]
	v_cvt_pk_bf16_f32 v104, v108, v109
	v_cvt_pk_bf16_f32 v105, v110, v111
	v_cvt_pk_bf16_f32 v106, v124, v125
	v_cvt_pk_bf16_f32 v107, v120, v121
	global_store_dwordx4 v[136:137], v[104:107], off offset:256
	s_nop 0
	v_pk_add_f32 v[102:103], v[102:103], v[118:119]
	v_pk_add_f32 v[100:101], v[100:101], v[116:117]
	v_add_u32_e32 v104, v128, v131
	v_ashrrev_i32_e32 v105, 31, v104
	v_lshlrev_b64 v[104:105], 15, v[104:105]
	v_or3_b32 v104, v104, v138, v129
	v_lshlrev_b64 v[104:105], 7, v[104:105]
	v_lshl_add_u64 v[104:105], s[92:93], 0, v[104:105]
	v_lshl_add_u64 v[104:105], v[104:105], 0, v[122:123]
	v_lshl_add_u64 v[224:225], v[104:105], 0, v[252:253]
	s_nop 0
	v_mov_b32_dpp v245, v108 quad_perm:[1,0,3,2] row_mask:0xf bank_mask:0xf
	v_mov_b32_dpp v246, v109 quad_perm:[1,0,3,2] row_mask:0xf bank_mask:0xf
	v_cndmask_b32_e64 v247, v108, v246, s[96:97]
	v_cndmask_b32_e64 v248, v245, v109, s[96:97]
	v_cvt_pk_bf16_f32 v247, v247, v248
	global_store_dword v[224:225], v247, off
	v_lshl_add_u64 v[224:225], v[224:225], 0, s[98:99]
	v_mov_b32_dpp v245, v110 quad_perm:[1,0,3,2] row_mask:0xf bank_mask:0xf
	v_mov_b32_dpp v246, v111 quad_perm:[1,0,3,2] row_mask:0xf bank_mask:0xf
	v_cndmask_b32_e64 v247, v110, v246, s[96:97]
	v_cndmask_b32_e64 v248, v245, v111, s[96:97]
	v_cvt_pk_bf16_f32 v247, v247, v248
	global_store_dword v[224:225], v247, off
	v_lshl_add_u64 v[224:225], v[224:225], 0, s[98:99]
	v_mov_b32_dpp v245, v124 quad_perm:[1,0,3,2] row_mask:0xf bank_mask:0xf
	v_mov_b32_dpp v246, v125 quad_perm:[1,0,3,2] row_mask:0xf bank_mask:0xf
	v_cndmask_b32_e64 v247, v124, v246, s[96:97]
	v_cndmask_b32_e64 v248, v245, v125, s[96:97]
	v_cvt_pk_bf16_f32 v247, v247, v248
	global_store_dword v[224:225], v247, off
	v_lshl_add_u64 v[224:225], v[224:225], 0, s[98:99]
	v_mov_b32_dpp v245, v120 quad_perm:[1,0,3,2] row_mask:0xf bank_mask:0xf
	v_mov_b32_dpp v246, v121 quad_perm:[1,0,3,2] row_mask:0xf bank_mask:0xf
	v_cndmask_b32_e64 v247, v120, v246, s[96:97]
	v_cndmask_b32_e64 v248, v245, v121, s[96:97]
	v_cvt_pk_bf16_f32 v247, v247, v248
	global_store_dword v[224:225], v247, off
	v_pk_add_f32 v[106:107], v[90:91], v[114:115]
	v_add_u32_e32 v104, 32, v162
	v_ashrrev_i32_e32 v105, 31, v104
	v_lshlrev_b64 v[110:111], 11, v[104:105]
	v_pk_add_f32 v[108:109], v[88:89], v[112:113]
	v_lshl_add_u64 v[110:111], s[18:19], 0, v[110:111]
	v_cvt_pk_bf16_f32 v88, v100, v101
	v_cvt_pk_bf16_f32 v89, v102, v103
	v_cvt_pk_bf16_f32 v90, v108, v109
	v_cvt_pk_bf16_f32 v91, v106, v107
	v_lshl_add_u64 v[110:111], v[110:111], 0, v[166:167]
	global_store_dwordx4 v[110:111], v[88:91], off
	s_nop 0
	v_pk_add_f32 v[86:87], v[86:87], v[98:99]
	v_ashrrev_i32_e32 v88, 11, v104
	v_and_b32_e32 v105, -4, v88
	v_add_u32_e32 v88, v163, v105
	v_ashrrev_i32_e32 v89, 31, v88
	v_lshlrev_b32_e32 v90, 2, v104
	v_lshlrev_b64 v[88:89], 15, v[88:89]
	v_and_b32_e32 v120, 0x7f00, v90
	v_or3_b32 v88, v88, v120, v165
	v_lshlrev_b64 v[88:89], 7, v[88:89]
	v_and_b32_e32 v90, 63, v104
	v_lshl_add_u64 v[88:89], s[92:93], 0, v[88:89]
	v_lshlrev_b32_e32 v90, 1, v90
	v_mov_b32_e32 v91, v153
	v_lshl_add_u64 v[88:89], v[88:89], 0, v[90:91]
	v_lshl_add_u64 v[224:225], v[88:89], 0, v[252:253]
	s_nop 0
	v_mov_b32_dpp v245, v100 quad_perm:[1,0,3,2] row_mask:0xf bank_mask:0xf
	v_mov_b32_dpp v246, v101 quad_perm:[1,0,3,2] row_mask:0xf bank_mask:0xf
	v_cndmask_b32_e64 v247, v100, v246, s[96:97]
	v_cndmask_b32_e64 v248, v245, v101, s[96:97]
	v_cvt_pk_bf16_f32 v247, v247, v248
	global_store_dword v[224:225], v247, off
	v_lshl_add_u64 v[224:225], v[224:225], 0, s[98:99]
; DI unsigned short f2bf(float x) { return (unsigned short)(pk2(x, 0.f) & 0xffffu); }
; DI uint4 pk8(f32x4 a, f32x4 b) { return make_uint4(pk2(a[0], a[1]), pk2(a[2], a[3]), pk2(b[0], b[1]), pk2(b[2], b[3])); }
;     DI void operator()(const f32x4 (&acc)[2][2][4][2], const pg8::Unit& u, int wr, int wc, int fr, int fq) const {
;     ...
;         if (pn < 4) {
; #pragma unroll
;             for (int i = 0; i < 16; ++i) {
;                 const int ai = TILE_AI(i), m = TILE_M(i), bj = TILE_BJ(i);
;                 const int t = t0 + ai * 128 + m * 16, col = colb + bj * 128;
;                 const f32x4 v0 = acc[ai][bj][m][0] + bia[bj][0], v1 = acc[ai][bj][m][1] + bia[bj][1];
;                 *(uint4*)(xm + (size_t)t * 1024 + col) = pk8(v0, v1);
;                 const int b = t >> 13, sidx = t & 8191;
;                 bf16_t* tp = xmT + ((((size_t)(b * 4 + (col >> 8)) * 128 + (sidx >> 6)) * 256 + (col & 255)) * 64) + (sidx & 63);
; #pragma unroll
;                 for (int r = 0; r < 4; ++r) { *tp = f2bf(v0[r]); tp += 64; asm volatile("" : "+v"(tp)); }
; #pragma unroll
;                 for (int r = 0; r < 4; ++r) { *tp = f2bf(v1[r]); tp += 64; asm volatile("" : "+v"(tp)); }
;             }
	v_mov_b32_dpp v245, v102 quad_perm:[1,0,3,2] row_mask:0xf bank_mask:0xf
	v_mov_b32_dpp v246, v103 quad_perm:[1,0,3,2] row_mask:0xf bank_mask:0xf
	v_cndmask_b32_e64 v247, v102, v246, s[96:97]
	v_cndmask_b32_e64 v248, v245, v103, s[96:97]
	v_cvt_pk_bf16_f32 v247, v247, v248
	global_store_dword v[224:225], v247, off
	v_lshl_add_u64 v[224:225], v[224:225], 0, s[98:99]
	v_mov_b32_dpp v245, v108 quad_perm:[1,0,3,2] row_mask:0xf bank_mask:0xf
	v_mov_b32_dpp v246, v109 quad_perm:[1,0,3,2] row_mask:0xf bank_mask:0xf
	v_cndmask_b32_e64 v247, v108, v246, s[96:97]
	v_cndmask_b32_e64 v248, v245, v109, s[96:97]
	v_cvt_pk_bf16_f32 v247, v247, v248
	global_store_dword v[224:225], v247, off
	v_lshl_add_u64 v[224:225], v[224:225], 0, s[98:99]
	v_mov_b32_dpp v245, v106 quad_perm:[1,0,3,2] row_mask:0xf bank_mask:0xf
	v_mov_b32_dpp v246, v107 quad_perm:[1,0,3,2] row_mask:0xf bank_mask:0xf
	v_cndmask_b32_e64 v247, v106, v246, s[96:97]
	v_cndmask_b32_e64 v248, v245, v107, s[96:97]
	v_cvt_pk_bf16_f32 v247, v247, v248
	global_store_dword v[224:225], v247, off
	v_pk_add_f32 v[84:85], v[84:85], v[96:97]
	v_pk_add_f32 v[88:89], v[82:83], v[94:95]
	v_pk_add_f32 v[100:101], v[80:81], v[92:93]
	v_cvt_pk_bf16_f32 v80, v84, v85
	v_cvt_pk_bf16_f32 v81, v86, v87
	v_cvt_pk_bf16_f32 v82, v100, v101
	v_cvt_pk_bf16_f32 v83, v88, v89
	global_store_dwordx4 v[110:111], v[80:83], off offset:256
	s_nop 0
	v_pk_add_f32 v[78:79], v[78:79], v[118:119]
	v_pk_add_f32 v[76:77], v[76:77], v[116:117]
	v_add_u32_e32 v80, v128, v105
	v_ashrrev_i32_e32 v81, 31, v80
	v_lshlrev_b64 v[80:81], 15, v[80:81]
	v_or3_b32 v80, v80, v120, v129
	v_lshlrev_b64 v[80:81], 7, v[80:81]
	v_lshl_add_u64 v[80:81], s[92:93], 0, v[80:81]
	v_lshl_add_u64 v[80:81], v[80:81], 0, v[90:91]
	v_lshl_add_u64 v[224:225], v[80:81], 0, v[252:253]
	s_nop 0
	v_mov_b32_dpp v245, v84 quad_perm:[1,0,3,2] row_mask:0xf bank_mask:0xf
	v_mov_b32_dpp v246, v85 quad_perm:[1,0,3,2] row_mask:0xf bank_mask:0xf
	v_cndmask_b32_e64 v247, v84, v246, s[96:97]
	v_cndmask_b32_e64 v248, v245, v85, s[96:97]
	v_cvt_pk_bf16_f32 v247, v247, v248
	global_store_dword v[224:225], v247, off
	v_lshl_add_u64 v[224:225], v[224:225], 0, s[98:99]
	v_mov_b32_dpp v245, v86 quad_perm:[1,0,3,2] row_mask:0xf bank_mask:0xf
	v_mov_b32_dpp v246, v87 quad_perm:[1,0,3,2] row_mask:0xf bank_mask:0xf
	v_cndmask_b32_e64 v247, v86, v246, s[96:97]
	v_cndmask_b32_e64 v248, v245, v87, s[96:97]
	v_cvt_pk_bf16_f32 v247, v247, v248
	global_store_dword v[224:225], v247, off
	v_lshl_add_u64 v[224:225], v[224:225], 0, s[98:99]
	v_mov_b32_dpp v245, v100 quad_perm:[1,0,3,2] row_mask:0xf bank_mask:0xf
	v_mov_b32_dpp v246, v101 quad_perm:[1,0,3,2] row_mask:0xf bank_mask:0xf
	v_cndmask_b32_e64 v247, v100, v246, s[96:97]
	v_cndmask_b32_e64 v248, v245, v101, s[96:97]
	v_cvt_pk_bf16_f32 v247, v247, v248
	global_store_dword v[224:225], v247, off
	v_lshl_add_u64 v[224:225], v[224:225], 0, s[98:99]
	v_mov_b32_dpp v245, v88 quad_perm:[1,0,3,2] row_mask:0xf bank_mask:0xf
	v_mov_b32_dpp v246, v89 quad_perm:[1,0,3,2] row_mask:0xf bank_mask:0xf
	v_cndmask_b32_e64 v247, v88, v246, s[96:97]
	v_cndmask_b32_e64 v248, v245, v89, s[96:97]
	v_cvt_pk_bf16_f32 v247, v247, v248
	global_store_dword v[224:225], v247, off
	v_pk_add_f32 v[82:83], v[74:75], v[114:115]
	v_add_u32_e32 v80, 48, v162
	v_ashrrev_i32_e32 v81, 31, v80
	v_lshlrev_b64 v[86:87], 11, v[80:81]
	v_pk_add_f32 v[84:85], v[72:73], v[112:113]
	v_lshl_add_u64 v[86:87], s[18:19], 0, v[86:87]
	v_cvt_pk_bf16_f32 v72, v76, v77
	v_cvt_pk_bf16_f32 v73, v78, v79
	v_cvt_pk_bf16_f32 v74, v84, v85
	v_cvt_pk_bf16_f32 v75, v82, v83
	v_lshl_add_u64 v[86:87], v[86:87], 0, v[166:167]
	global_store_dwordx4 v[86:87], v[72:75], off
	s_nop 0
	v_pk_add_f32 v[70:71], v[70:71], v[98:99]
	v_ashrrev_i32_e32 v72, 11, v80
	v_and_b32_e32 v81, -4, v72
	v_add_u32_e32 v72, v163, v81
	v_ashrrev_i32_e32 v73, 31, v72
	v_lshlrev_b32_e32 v74, 2, v80
	v_lshlrev_b64 v[72:73], 15, v[72:73]
	v_and_b32_e32 v88, 0x7f00, v74
	v_or3_b32 v72, v72, v88, v165
	v_lshlrev_b64 v[72:73], 7, v[72:73]
	v_and_b32_e32 v74, 63, v80
	v_lshl_add_u64 v[72:73], s[92:93], 0, v[72:73]
	v_lshlrev_b32_e32 v74, 1, v74
	v_mov_b32_e32 v75, v153
	v_lshl_add_u64 v[72:73], v[72:73], 0, v[74:75]
	v_lshl_add_u64 v[224:225], v[72:73], 0, v[252:253]
	s_nop 0
	v_mov_b32_dpp v245, v76 quad_perm:[1,0,3,2] row_mask:0xf bank_mask:0xf
	v_mov_b32_dpp v246, v77 quad_perm:[1,0,3,2] row_mask:0xf bank_mask:0xf
	v_cndmask_b32_e64 v247, v76, v246, s[96:97]
	v_cndmask_b32_e64 v248, v245, v77, s[96:97]
	v_cvt_pk_bf16_f32 v247, v247, v248
	global_store_dword v[224:225], v247, off
	v_lshl_add_u64 v[224:225], v[224:225], 0, s[98:99]
	v_mov_b32_dpp v245, v78 quad_perm:[1,0,3,2] row_mask:0xf bank_mask:0xf
	v_mov_b32_dpp v246, v79 quad_perm:[1,0,3,2] row_mask:0xf bank_mask:0xf
	v_cndmask_b32_e64 v247, v78, v246, s[96:97]
	v_cndmask_b32_e64 v248, v245, v79, s[96:97]
	v_cvt_pk_bf16_f32 v247, v247, v248
	global_store_dword v[224:225], v247, off
	v_lshl_add_u64 v[224:225], v[224:225], 0, s[98:99]
	v_mov_b32_dpp v245, v84 quad_perm:[1,0,3,2] row_mask:0xf bank_mask:0xf
	v_mov_b32_dpp v246, v85 quad_perm:[1,0,3,2] row_mask:0xf bank_mask:0xf
	v_cndmask_b32_e64 v247, v84, v246, s[96:97]
	v_cndmask_b32_e64 v248, v245, v85, s[96:97]
	v_cvt_pk_bf16_f32 v247, v247, v248
	global_store_dword v[224:225], v247, off
	v_lshl_add_u64 v[224:225], v[224:225], 0, s[98:99]
	v_mov_b32_dpp v245, v82 quad_perm:[1,0,3,2] row_mask:0xf bank_mask:0xf
	v_mov_b32_dpp v246, v83 quad_perm:[1,0,3,2] row_mask:0xf bank_mask:0xf
	v_cndmask_b32_e64 v247, v82, v246, s[96:97]
	v_cndmask_b32_e64 v248, v245, v83, s[96:97]
	v_cvt_pk_bf16_f32 v247, v247, v248
; DI unsigned short f2bf(float x) { return (unsigned short)(pk2(x, 0.f) & 0xffffu); }
; DI uint4 pk8(f32x4 a, f32x4 b) { return make_uint4(pk2(a[0], a[1]), pk2(a[2], a[3]), pk2(b[0], b[1]), pk2(b[2], b[3])); }
;     DI void operator()(const f32x4 (&acc)[2][2][4][2], const pg8::Unit& u, int wr, int wc, int fr, int fq) const {
;     ...
;         if (pn < 4) {
; #pragma unroll
;             for (int i = 0; i < 16; ++i) {
;                 const int ai = TILE_AI(i), m = TILE_M(i), bj = TILE_BJ(i);
;                 const int t = t0 + ai * 128 + m * 16, col = colb + bj * 128;
;                 const f32x4 v0 = acc[ai][bj][m][0] + bia[bj][0], v1 = acc[ai][bj][m][1] + bia[bj][1];
;                 *(uint4*)(xm + (size_t)t * 1024 + col) = pk8(v0, v1);
;                 const int b = t >> 13, sidx = t & 8191;
;                 bf16_t* tp = xmT + ((((size_t)(b * 4 + (col >> 8)) * 128 + (sidx >> 6)) * 256 + (col & 255)) * 64) + (sidx & 63);
; #pragma unroll
;                 for (int r = 0; r < 4; ++r) { *tp = f2bf(v0[r]); tp += 64; asm volatile("" : "+v"(tp)); }
; #pragma unroll
;                 for (int r = 0; r < 4; ++r) { *tp = f2bf(v1[r]); tp += 64; asm volatile("" : "+v"(tp)); }
;             }
	global_store_dword v[224:225], v247, off
	v_pk_add_f32 v[68:69], v[68:69], v[96:97]
	v_pk_add_f32 v[72:73], v[66:67], v[94:95]
	v_pk_add_f32 v[76:77], v[64:65], v[92:93]
	v_cvt_pk_bf16_f32 v64, v68, v69
	v_cvt_pk_bf16_f32 v65, v70, v71
	v_cvt_pk_bf16_f32 v66, v76, v77
	v_cvt_pk_bf16_f32 v67, v72, v73
	global_store_dwordx4 v[86:87], v[64:67], off offset:256
	s_nop 0
	v_pk_add_f32 v[62:63], v[62:63], v[118:119]
	v_pk_add_f32 v[60:61], v[60:61], v[116:117]
	v_add_u32_e32 v64, v128, v81
	v_ashrrev_i32_e32 v65, 31, v64
	v_lshlrev_b64 v[64:65], 15, v[64:65]
	v_or3_b32 v64, v64, v88, v129
	v_lshlrev_b64 v[64:65], 7, v[64:65]
	v_lshl_add_u64 v[64:65], s[92:93], 0, v[64:65]
	v_lshl_add_u64 v[64:65], v[64:65], 0, v[74:75]
	v_lshl_add_u64 v[224:225], v[64:65], 0, v[252:253]
	s_nop 0
	v_mov_b32_dpp v245, v68 quad_perm:[1,0,3,2] row_mask:0xf bank_mask:0xf
	v_mov_b32_dpp v246, v69 quad_perm:[1,0,3,2] row_mask:0xf bank_mask:0xf
	v_cndmask_b32_e64 v247, v68, v246, s[96:97]
	v_cndmask_b32_e64 v248, v245, v69, s[96:97]
	v_cvt_pk_bf16_f32 v247, v247, v248
	global_store_dword v[224:225], v247, off
	v_lshl_add_u64 v[224:225], v[224:225], 0, s[98:99]
	v_mov_b32_dpp v245, v70 quad_perm:[1,0,3,2] row_mask:0xf bank_mask:0xf
	v_mov_b32_dpp v246, v71 quad_perm:[1,0,3,2] row_mask:0xf bank_mask:0xf
	v_cndmask_b32_e64 v247, v70, v246, s[96:97]
	v_cndmask_b32_e64 v248, v245, v71, s[96:97]
	v_cvt_pk_bf16_f32 v247, v247, v248
	global_store_dword v[224:225], v247, off
	v_lshl_add_u64 v[224:225], v[224:225], 0, s[98:99]
	v_mov_b32_dpp v245, v76 quad_perm:[1,0,3,2] row_mask:0xf bank_mask:0xf
	v_mov_b32_dpp v246, v77 quad_perm:[1,0,3,2] row_mask:0xf bank_mask:0xf
	v_cndmask_b32_e64 v247, v76, v246, s[96:97]
	v_cndmask_b32_e64 v248, v245, v77, s[96:97]
	v_cvt_pk_bf16_f32 v247, v247, v248
	global_store_dword v[224:225], v247, off
	v_lshl_add_u64 v[224:225], v[224:225], 0, s[98:99]
	v_mov_b32_dpp v245, v72 quad_perm:[1,0,3,2] row_mask:0xf bank_mask:0xf
	v_mov_b32_dpp v246, v73 quad_perm:[1,0,3,2] row_mask:0xf bank_mask:0xf
	v_cndmask_b32_e64 v247, v72, v246, s[96:97]
	v_cndmask_b32_e64 v248, v245, v73, s[96:97]
	v_cvt_pk_bf16_f32 v247, v247, v248
	global_store_dword v[224:225], v247, off
	v_pk_add_f32 v[66:67], v[58:59], v[114:115]
	v_add_u32_e32 v64, 0x80, v162
	v_ashrrev_i32_e32 v65, 31, v64
	v_lshlrev_b64 v[70:71], 11, v[64:65]
	v_pk_add_f32 v[68:69], v[56:57], v[112:113]
	v_lshl_add_u64 v[70:71], s[18:19], 0, v[70:71]
	v_cvt_pk_bf16_f32 v56, v60, v61
	v_cvt_pk_bf16_f32 v57, v62, v63
	v_cvt_pk_bf16_f32 v58, v68, v69
	v_cvt_pk_bf16_f32 v59, v66, v67
	v_lshl_add_u64 v[70:71], v[70:71], 0, v[166:167]
	global_store_dwordx4 v[70:71], v[56:59], off
	s_nop 0
	v_pk_add_f32 v[54:55], v[54:55], v[98:99]
	v_pk_add_f32 v[52:53], v[52:53], v[96:97]
	v_ashrrev_i32_e32 v56, 11, v64
	v_and_b32_e32 v65, -4, v56
	v_add_u32_e32 v56, v163, v65
	v_ashrrev_i32_e32 v57, 31, v56
	v_lshlrev_b32_e32 v58, 2, v64
	v_lshlrev_b64 v[56:57], 15, v[56:57]
	v_and_b32_e32 v64, 0x7f00, v58
	v_or3_b32 v56, v56, v64, v165
	v_lshlrev_b64 v[56:57], 7, v[56:57]
	v_lshl_add_u64 v[56:57], s[92:93], 0, v[56:57]
	v_lshl_add_u64 v[56:57], v[56:57], 0, v[152:153]
	v_lshl_add_u64 v[224:225], v[56:57], 0, v[252:253]
	s_nop 0
	v_mov_b32_dpp v245, v60 quad_perm:[1,0,3,2] row_mask:0xf bank_mask:0xf
	v_mov_b32_dpp v246, v61 quad_perm:[1,0,3,2] row_mask:0xf bank_mask:0xf
	v_cndmask_b32_e64 v247, v60, v246, s[96:97]
	v_cndmask_b32_e64 v248, v245, v61, s[96:97]
	v_cvt_pk_bf16_f32 v247, v247, v248
	global_store_dword v[224:225], v247, off
	v_lshl_add_u64 v[224:225], v[224:225], 0, s[98:99]
	v_mov_b32_dpp v245, v62 quad_perm:[1,0,3,2] row_mask:0xf bank_mask:0xf
	v_mov_b32_dpp v246, v63 quad_perm:[1,0,3,2] row_mask:0xf bank_mask:0xf
	v_cndmask_b32_e64 v247, v62, v246, s[96:97]
	v_cndmask_b32_e64 v248, v245, v63, s[96:97]
	v_cvt_pk_bf16_f32 v247, v247, v248
	global_store_dword v[224:225], v247, off
	v_lshl_add_u64 v[224:225], v[224:225], 0, s[98:99]
	v_mov_b32_dpp v245, v68 quad_perm:[1,0,3,2] row_mask:0xf bank_mask:0xf
	v_mov_b32_dpp v246, v69 quad_perm:[1,0,3,2] row_mask:0xf bank_mask:0xf
	v_cndmask_b32_e64 v247, v68, v246, s[96:97]
	v_cndmask_b32_e64 v248, v245, v69, s[96:97]
	v_cvt_pk_bf16_f32 v247, v247, v248
	global_store_dword v[224:225], v247, off
	v_lshl_add_u64 v[224:225], v[224:225], 0, s[98:99]
	v_mov_b32_dpp v245, v66 quad_perm:[1,0,3,2] row_mask:0xf bank_mask:0xf
	v_mov_b32_dpp v246, v67 quad_perm:[1,0,3,2] row_mask:0xf bank_mask:0xf
	v_cndmask_b32_e64 v247, v66, v246, s[96:97]
	v_cndmask_b32_e64 v248, v245, v67, s[96:97]
	v_cvt_pk_bf16_f32 v247, v247, v248
	global_store_dword v[224:225], v247, off
	v_pk_add_f32 v[58:59], v[48:49], v[92:93]
	v_pk_add_f32 v[56:57], v[50:51], v[94:95]
	v_cvt_pk_bf16_f32 v48, v52, v53
	v_cvt_pk_bf16_f32 v49, v54, v55
	v_cvt_pk_bf16_f32 v50, v58, v59
	v_cvt_pk_bf16_f32 v51, v56, v57
	global_store_dwordx4 v[70:71], v[48:51], off offset:256
	s_nop 0
	v_pk_add_f32 v[46:47], v[46:47], v[118:119]
	v_pk_add_f32 v[44:45], v[44:45], v[116:117]
	v_add_u32_e32 v48, v128, v65
	v_ashrrev_i32_e32 v49, 31, v48
	v_lshlrev_b64 v[48:49], 15, v[48:49]
	v_or3_b32 v48, v48, v64, v129
	v_lshlrev_b64 v[48:49], 7, v[48:49]
	v_lshl_add_u64 v[48:49], s[92:93], 0, v[48:49]
	v_lshl_add_u64 v[48:49], v[48:49], 0, v[152:153]
	v_lshl_add_u64 v[224:225], v[48:49], 0, v[252:253]
	s_nop 0
	v_mov_b32_dpp v245, v52 quad_perm:[1,0,3,2] row_mask:0xf bank_mask:0xf
	v_mov_b32_dpp v246, v53 quad_perm:[1,0,3,2] row_mask:0xf bank_mask:0xf
	v_cndmask_b32_e64 v247, v52, v246, s[96:97]
	v_cndmask_b32_e64 v248, v245, v53, s[96:97]
	v_cvt_pk_bf16_f32 v247, v247, v248
	global_store_dword v[224:225], v247, off
; DI unsigned short f2bf(float x) { return (unsigned short)(pk2(x, 0.f) & 0xffffu); }
; DI uint4 pk8(f32x4 a, f32x4 b) { return make_uint4(pk2(a[0], a[1]), pk2(a[2], a[3]), pk2(b[0], b[1]), pk2(b[2], b[3])); }
;     DI void operator()(const f32x4 (&acc)[2][2][4][2], const pg8::Unit& u, int wr, int wc, int fr, int fq) const {
;     ...
;         if (pn < 4) {
; #pragma unroll
;             for (int i = 0; i < 16; ++i) {
;                 const int ai = TILE_AI(i), m = TILE_M(i), bj = TILE_BJ(i);
;                 const int t = t0 + ai * 128 + m * 16, col = colb + bj * 128;
;                 const f32x4 v0 = acc[ai][bj][m][0] + bia[bj][0], v1 = acc[ai][bj][m][1] + bia[bj][1];
;                 *(uint4*)(xm + (size_t)t * 1024 + col) = pk8(v0, v1);
;                 const int b = t >> 13, sidx = t & 8191;
;                 bf16_t* tp = xmT + ((((size_t)(b * 4 + (col >> 8)) * 128 + (sidx >> 6)) * 256 + (col & 255)) * 64) + (sidx & 63);
; #pragma unroll
;                 for (int r = 0; r < 4; ++r) { *tp = f2bf(v0[r]); tp += 64; asm volatile("" : "+v"(tp)); }
; #pragma unroll
;                 for (int r = 0; r < 4; ++r) { *tp = f2bf(v1[r]); tp += 64; asm volatile("" : "+v"(tp)); }
;             }
	v_lshl_add_u64 v[224:225], v[224:225], 0, s[98:99]
	v_mov_b32_dpp v245, v54 quad_perm:[1,0,3,2] row_mask:0xf bank_mask:0xf
	v_mov_b32_dpp v246, v55 quad_perm:[1,0,3,2] row_mask:0xf bank_mask:0xf
	v_cndmask_b32_e64 v247, v54, v246, s[96:97]
	v_cndmask_b32_e64 v248, v245, v55, s[96:97]
	v_cvt_pk_bf16_f32 v247, v247, v248
	global_store_dword v[224:225], v247, off
	v_lshl_add_u64 v[224:225], v[224:225], 0, s[98:99]
	v_mov_b32_dpp v245, v58 quad_perm:[1,0,3,2] row_mask:0xf bank_mask:0xf
	v_mov_b32_dpp v246, v59 quad_perm:[1,0,3,2] row_mask:0xf bank_mask:0xf
	v_cndmask_b32_e64 v247, v58, v246, s[96:97]
	v_cndmask_b32_e64 v248, v245, v59, s[96:97]
	v_cvt_pk_bf16_f32 v247, v247, v248
	global_store_dword v[224:225], v247, off
	v_lshl_add_u64 v[224:225], v[224:225], 0, s[98:99]
	v_mov_b32_dpp v245, v56 quad_perm:[1,0,3,2] row_mask:0xf bank_mask:0xf
	v_mov_b32_dpp v246, v57 quad_perm:[1,0,3,2] row_mask:0xf bank_mask:0xf
	v_cndmask_b32_e64 v247, v56, v246, s[96:97]
	v_cndmask_b32_e64 v248, v245, v57, s[96:97]
	v_cvt_pk_bf16_f32 v247, v247, v248
	global_store_dword v[224:225], v247, off
	v_pk_add_f32 v[50:51], v[42:43], v[114:115]
	v_add_u32_e32 v48, 0x90, v162
	v_ashrrev_i32_e32 v49, 31, v48
	v_lshlrev_b64 v[54:55], 11, v[48:49]
	v_pk_add_f32 v[52:53], v[40:41], v[112:113]
	v_lshl_add_u64 v[54:55], s[18:19], 0, v[54:55]
	v_cvt_pk_bf16_f32 v40, v44, v45
	v_cvt_pk_bf16_f32 v41, v46, v47
	v_cvt_pk_bf16_f32 v42, v52, v53
	v_cvt_pk_bf16_f32 v43, v50, v51
	v_lshl_add_u64 v[54:55], v[54:55], 0, v[166:167]
	global_store_dwordx4 v[54:55], v[40:43], off
	s_nop 0
	v_pk_add_f32 v[38:39], v[38:39], v[98:99]
	v_pk_add_f32 v[36:37], v[36:37], v[96:97]
	v_ashrrev_i32_e32 v40, 11, v48
	v_and_b32_e32 v49, -4, v40
	v_add_u32_e32 v40, v163, v49
	v_ashrrev_i32_e32 v41, 31, v40
	v_lshlrev_b32_e32 v42, 2, v48
	v_lshlrev_b64 v[40:41], 15, v[40:41]
	v_and_b32_e32 v56, 0x7f00, v42
	v_or3_b32 v40, v40, v56, v165
	v_lshlrev_b64 v[40:41], 7, v[40:41]
	v_and_b32_e32 v42, 63, v48
	v_lshl_add_u64 v[40:41], s[92:93], 0, v[40:41]
	v_lshlrev_b32_e32 v152, 1, v42
	v_lshl_add_u64 v[40:41], v[40:41], 0, v[152:153]
	v_lshl_add_u64 v[224:225], v[40:41], 0, v[252:253]
	s_nop 0
	v_mov_b32_dpp v245, v44 quad_perm:[1,0,3,2] row_mask:0xf bank_mask:0xf
	v_mov_b32_dpp v246, v45 quad_perm:[1,0,3,2] row_mask:0xf bank_mask:0xf
	v_cndmask_b32_e64 v247, v44, v246, s[96:97]
	v_cndmask_b32_e64 v248, v245, v45, s[96:97]
	v_cvt_pk_bf16_f32 v247, v247, v248
	global_store_dword v[224:225], v247, off
	v_lshl_add_u64 v[224:225], v[224:225], 0, s[98:99]
	v_mov_b32_dpp v245, v46 quad_perm:[1,0,3,2] row_mask:0xf bank_mask:0xf
	v_mov_b32_dpp v246, v47 quad_perm:[1,0,3,2] row_mask:0xf bank_mask:0xf
	v_cndmask_b32_e64 v247, v46, v246, s[96:97]
	v_cndmask_b32_e64 v248, v245, v47, s[96:97]
	v_cvt_pk_bf16_f32 v247, v247, v248
	global_store_dword v[224:225], v247, off
	v_lshl_add_u64 v[224:225], v[224:225], 0, s[98:99]
	v_mov_b32_dpp v245, v52 quad_perm:[1,0,3,2] row_mask:0xf bank_mask:0xf
	v_mov_b32_dpp v246, v53 quad_perm:[1,0,3,2] row_mask:0xf bank_mask:0xf
	v_cndmask_b32_e64 v247, v52, v246, s[96:97]
	v_cndmask_b32_e64 v248, v245, v53, s[96:97]
	v_cvt_pk_bf16_f32 v247, v247, v248
	global_store_dword v[224:225], v247, off
	v_lshl_add_u64 v[224:225], v[224:225], 0, s[98:99]
	v_mov_b32_dpp v245, v50 quad_perm:[1,0,3,2] row_mask:0xf bank_mask:0xf
	v_mov_b32_dpp v246, v51 quad_perm:[1,0,3,2] row_mask:0xf bank_mask:0xf
	v_cndmask_b32_e64 v247, v50, v246, s[96:97]
	v_cndmask_b32_e64 v248, v245, v51, s[96:97]
	v_cvt_pk_bf16_f32 v247, v247, v248
	global_store_dword v[224:225], v247, off
	v_pk_add_f32 v[42:43], v[32:33], v[92:93]
	v_pk_add_f32 v[40:41], v[34:35], v[94:95]
	v_cvt_pk_bf16_f32 v32, v36, v37
	v_cvt_pk_bf16_f32 v33, v38, v39
	v_cvt_pk_bf16_f32 v34, v42, v43
	v_cvt_pk_bf16_f32 v35, v40, v41
	global_store_dwordx4 v[54:55], v[32:35], off offset:256
	s_nop 0
	v_pk_add_f32 v[30:31], v[30:31], v[118:119]
	v_pk_add_f32 v[28:29], v[28:29], v[116:117]
	v_add_u32_e32 v32, v128, v49
	v_ashrrev_i32_e32 v33, 31, v32
	v_lshlrev_b64 v[32:33], 15, v[32:33]
	v_or3_b32 v32, v32, v56, v129
	v_lshlrev_b64 v[32:33], 7, v[32:33]
	v_lshl_add_u64 v[32:33], s[92:93], 0, v[32:33]
	v_lshl_add_u64 v[32:33], v[32:33], 0, v[152:153]
	v_lshl_add_u64 v[224:225], v[32:33], 0, v[252:253]
	s_nop 0
	v_mov_b32_dpp v245, v36 quad_perm:[1,0,3,2] row_mask:0xf bank_mask:0xf
	v_mov_b32_dpp v246, v37 quad_perm:[1,0,3,2] row_mask:0xf bank_mask:0xf
	v_cndmask_b32_e64 v247, v36, v246, s[96:97]
	v_cndmask_b32_e64 v248, v245, v37, s[96:97]
	v_cvt_pk_bf16_f32 v247, v247, v248
	global_store_dword v[224:225], v247, off
	v_lshl_add_u64 v[224:225], v[224:225], 0, s[98:99]
	v_mov_b32_dpp v245, v38 quad_perm:[1,0,3,2] row_mask:0xf bank_mask:0xf
	v_mov_b32_dpp v246, v39 quad_perm:[1,0,3,2] row_mask:0xf bank_mask:0xf
	v_cndmask_b32_e64 v247, v38, v246, s[96:97]
	v_cndmask_b32_e64 v248, v245, v39, s[96:97]
	v_cvt_pk_bf16_f32 v247, v247, v248
	global_store_dword v[224:225], v247, off
	v_lshl_add_u64 v[224:225], v[224:225], 0, s[98:99]
	v_mov_b32_dpp v245, v42 quad_perm:[1,0,3,2] row_mask:0xf bank_mask:0xf
	v_mov_b32_dpp v246, v43 quad_perm:[1,0,3,2] row_mask:0xf bank_mask:0xf
	v_cndmask_b32_e64 v247, v42, v246, s[96:97]
	v_cndmask_b32_e64 v248, v245, v43, s[96:97]
	v_cvt_pk_bf16_f32 v247, v247, v248
	global_store_dword v[224:225], v247, off
	v_lshl_add_u64 v[224:225], v[224:225], 0, s[98:99]
	v_mov_b32_dpp v245, v40 quad_perm:[1,0,3,2] row_mask:0xf bank_mask:0xf
	v_mov_b32_dpp v246, v41 quad_perm:[1,0,3,2] row_mask:0xf bank_mask:0xf
	v_cndmask_b32_e64 v247, v40, v246, s[96:97]
	v_cndmask_b32_e64 v248, v245, v41, s[96:97]
	v_cvt_pk_bf16_f32 v247, v247, v248
; DI unsigned short f2bf(float x) { return (unsigned short)(pk2(x, 0.f) & 0xffffu); }
; DI uint4 pk8(f32x4 a, f32x4 b) { return make_uint4(pk2(a[0], a[1]), pk2(a[2], a[3]), pk2(b[0], b[1]), pk2(b[2], b[3])); }
;     DI void operator()(const f32x4 (&acc)[2][2][4][2], const pg8::Unit& u, int wr, int wc, int fr, int fq) const {
;     ...
;         if (pn < 4) {
; #pragma unroll
;             for (int i = 0; i < 16; ++i) {
;                 const int ai = TILE_AI(i), m = TILE_M(i), bj = TILE_BJ(i);
;                 const int t = t0 + ai * 128 + m * 16, col = colb + bj * 128;
;                 const f32x4 v0 = acc[ai][bj][m][0] + bia[bj][0], v1 = acc[ai][bj][m][1] + bia[bj][1];
;                 *(uint4*)(xm + (size_t)t * 1024 + col) = pk8(v0, v1);
;                 const int b = t >> 13, sidx = t & 8191;
;                 bf16_t* tp = xmT + ((((size_t)(b * 4 + (col >> 8)) * 128 + (sidx >> 6)) * 256 + (col & 255)) * 64) + (sidx & 63);
; #pragma unroll
;                 for (int r = 0; r < 4; ++r) { *tp = f2bf(v0[r]); tp += 64; asm volatile("" : "+v"(tp)); }
; #pragma unroll
;                 for (int r = 0; r < 4; ++r) { *tp = f2bf(v1[r]); tp += 64; asm volatile("" : "+v"(tp)); }
;             }
	global_store_dword v[224:225], v247, off
	v_pk_add_f32 v[34:35], v[26:27], v[114:115]
	v_add_u32_e32 v32, 0xa0, v162
	v_ashrrev_i32_e32 v33, 31, v32
	v_lshlrev_b64 v[38:39], 11, v[32:33]
	v_pk_add_f32 v[36:37], v[24:25], v[112:113]
	v_lshl_add_u64 v[38:39], s[18:19], 0, v[38:39]
	v_cvt_pk_bf16_f32 v24, v28, v29
	v_cvt_pk_bf16_f32 v25, v30, v31
	v_cvt_pk_bf16_f32 v26, v36, v37
	v_cvt_pk_bf16_f32 v27, v34, v35
	v_lshl_add_u64 v[38:39], v[38:39], 0, v[166:167]
	global_store_dwordx4 v[38:39], v[24:27], off
	s_nop 0
	v_pk_add_f32 v[22:23], v[22:23], v[98:99]
	v_pk_add_f32 v[20:21], v[20:21], v[96:97]
	v_ashrrev_i32_e32 v24, 11, v32
	v_and_b32_e32 v33, -4, v24
	v_add_u32_e32 v24, v163, v33
	v_ashrrev_i32_e32 v25, 31, v24
	v_lshlrev_b32_e32 v26, 2, v32
	v_lshlrev_b64 v[24:25], 15, v[24:25]
	v_and_b32_e32 v40, 0x7f00, v26
	v_or3_b32 v24, v24, v40, v165
	v_lshlrev_b64 v[24:25], 7, v[24:25]
	v_and_b32_e32 v26, 63, v32
	v_lshl_add_u64 v[24:25], s[92:93], 0, v[24:25]
	v_lshlrev_b32_e32 v152, 1, v26
	v_lshl_add_u64 v[24:25], v[24:25], 0, v[152:153]
	v_lshl_add_u64 v[224:225], v[24:25], 0, v[252:253]
	s_nop 0
	v_mov_b32_dpp v245, v28 quad_perm:[1,0,3,2] row_mask:0xf bank_mask:0xf
	v_mov_b32_dpp v246, v29 quad_perm:[1,0,3,2] row_mask:0xf bank_mask:0xf
	v_cndmask_b32_e64 v247, v28, v246, s[96:97]
	v_cndmask_b32_e64 v248, v245, v29, s[96:97]
	v_cvt_pk_bf16_f32 v247, v247, v248
	global_store_dword v[224:225], v247, off
	v_lshl_add_u64 v[224:225], v[224:225], 0, s[98:99]
	v_mov_b32_dpp v245, v30 quad_perm:[1,0,3,2] row_mask:0xf bank_mask:0xf
	v_mov_b32_dpp v246, v31 quad_perm:[1,0,3,2] row_mask:0xf bank_mask:0xf
	v_cndmask_b32_e64 v247, v30, v246, s[96:97]
	v_cndmask_b32_e64 v248, v245, v31, s[96:97]
	v_cvt_pk_bf16_f32 v247, v247, v248
	global_store_dword v[224:225], v247, off
	v_lshl_add_u64 v[224:225], v[224:225], 0, s[98:99]
	v_mov_b32_dpp v245, v36 quad_perm:[1,0,3,2] row_mask:0xf bank_mask:0xf
	v_mov_b32_dpp v246, v37 quad_perm:[1,0,3,2] row_mask:0xf bank_mask:0xf
	v_cndmask_b32_e64 v247, v36, v246, s[96:97]
	v_cndmask_b32_e64 v248, v245, v37, s[96:97]
	v_cvt_pk_bf16_f32 v247, v247, v248
	global_store_dword v[224:225], v247, off
	v_lshl_add_u64 v[224:225], v[224:225], 0, s[98:99]
	v_mov_b32_dpp v245, v34 quad_perm:[1,0,3,2] row_mask:0xf bank_mask:0xf
	v_mov_b32_dpp v246, v35 quad_perm:[1,0,3,2] row_mask:0xf bank_mask:0xf
	v_cndmask_b32_e64 v247, v34, v246, s[96:97]
	v_cndmask_b32_e64 v248, v245, v35, s[96:97]
	v_cvt_pk_bf16_f32 v247, v247, v248
	global_store_dword v[224:225], v247, off
	v_pk_add_f32 v[26:27], v[16:17], v[92:93]
	v_pk_add_f32 v[24:25], v[18:19], v[94:95]
	v_cvt_pk_bf16_f32 v16, v20, v21
	v_cvt_pk_bf16_f32 v17, v22, v23
	v_cvt_pk_bf16_f32 v18, v26, v27
	v_cvt_pk_bf16_f32 v19, v24, v25
	global_store_dwordx4 v[38:39], v[16:19], off offset:256
	s_nop 0
	v_pk_add_f32 v[14:15], v[14:15], v[118:119]
	v_pk_add_f32 v[12:13], v[12:13], v[116:117]
	v_add_u32_e32 v16, v128, v33
	v_ashrrev_i32_e32 v17, 31, v16
	v_lshlrev_b64 v[16:17], 15, v[16:17]
	v_or3_b32 v16, v16, v40, v129
	v_lshlrev_b64 v[16:17], 7, v[16:17]
	v_lshl_add_u64 v[16:17], s[92:93], 0, v[16:17]
	v_lshl_add_u64 v[16:17], v[16:17], 0, v[152:153]
	v_lshl_add_u64 v[224:225], v[16:17], 0, v[252:253]
	s_nop 0
	v_mov_b32_dpp v245, v20 quad_perm:[1,0,3,2] row_mask:0xf bank_mask:0xf
	v_mov_b32_dpp v246, v21 quad_perm:[1,0,3,2] row_mask:0xf bank_mask:0xf
	v_cndmask_b32_e64 v247, v20, v246, s[96:97]
	v_cndmask_b32_e64 v248, v245, v21, s[96:97]
	v_cvt_pk_bf16_f32 v247, v247, v248
	global_store_dword v[224:225], v247, off
	v_lshl_add_u64 v[224:225], v[224:225], 0, s[98:99]
	v_mov_b32_dpp v245, v22 quad_perm:[1,0,3,2] row_mask:0xf bank_mask:0xf
	v_mov_b32_dpp v246, v23 quad_perm:[1,0,3,2] row_mask:0xf bank_mask:0xf
	v_cndmask_b32_e64 v247, v22, v246, s[96:97]
	v_cndmask_b32_e64 v248, v245, v23, s[96:97]
	v_cvt_pk_bf16_f32 v247, v247, v248
	global_store_dword v[224:225], v247, off
	v_lshl_add_u64 v[224:225], v[224:225], 0, s[98:99]
	v_mov_b32_dpp v245, v26 quad_perm:[1,0,3,2] row_mask:0xf bank_mask:0xf
	v_mov_b32_dpp v246, v27 quad_perm:[1,0,3,2] row_mask:0xf bank_mask:0xf
	v_cndmask_b32_e64 v247, v26, v246, s[96:97]
	v_cndmask_b32_e64 v248, v245, v27, s[96:97]
	v_cvt_pk_bf16_f32 v247, v247, v248
	global_store_dword v[224:225], v247, off
	v_lshl_add_u64 v[224:225], v[224:225], 0, s[98:99]
	v_mov_b32_dpp v245, v24 quad_perm:[1,0,3,2] row_mask:0xf bank_mask:0xf
	v_mov_b32_dpp v246, v25 quad_perm:[1,0,3,2] row_mask:0xf bank_mask:0xf
	v_cndmask_b32_e64 v247, v24, v246, s[96:97]
	v_cndmask_b32_e64 v248, v245, v25, s[96:97]
; DI unsigned short f2bf(float x) { return (unsigned short)(pk2(x, 0.f) & 0xffffu); }
; DI uint4 pk8(f32x4 a, f32x4 b) { return make_uint4(pk2(a[0], a[1]), pk2(a[2], a[3]), pk2(b[0], b[1]), pk2(b[2], b[3])); }
; template <class Epi>
; DI void gemm_phase(PG8_LAS unsigned char* lds, const Gemm g, const StaticOrder& S, const Epi& E) {
;     ...
;         if (!has_next) break;
;     DI void operator()(const f32x4 (&acc)[2][2][4][2], const pg8::Unit& u, int wr, int wc, int fr, int fq) const {
;     ...
;         if (pn < 4) {
; #pragma unroll
;             for (int i = 0; i < 16; ++i) {
;                 const int ai = TILE_AI(i), m = TILE_M(i), bj = TILE_BJ(i);
;                 const int t = t0 + ai * 128 + m * 16, col = colb + bj * 128;
;                 const f32x4 v0 = acc[ai][bj][m][0] + bia[bj][0], v1 = acc[ai][bj][m][1] + bia[bj][1];
;                 *(uint4*)(xm + (size_t)t * 1024 + col) = pk8(v0, v1);
;                 const int b = t >> 13, sidx = t & 8191;
;                 bf16_t* tp = xmT + ((((size_t)(b * 4 + (col >> 8)) * 128 + (sidx >> 6)) * 256 + (col & 255)) * 64) + (sidx & 63);
; #pragma unroll
;                 for (int r = 0; r < 4; ++r) { *tp = f2bf(v0[r]); tp += 64; asm volatile("" : "+v"(tp)); }
; #pragma unroll
;                 for (int r = 0; r < 4; ++r) { *tp = f2bf(v1[r]); tp += 64; asm volatile("" : "+v"(tp)); }
;             }
	v_cvt_pk_bf16_f32 v247, v247, v248
	global_store_dword v[224:225], v247, off
	v_pk_add_f32 v[18:19], v[10:11], v[114:115]
	v_add_u32_e32 v16, 0xb0, v162
	v_ashrrev_i32_e32 v17, 31, v16
	v_lshlrev_b64 v[22:23], 11, v[16:17]
	v_pk_add_f32 v[20:21], v[8:9], v[112:113]
	v_lshl_add_u64 v[22:23], s[18:19], 0, v[22:23]
	v_cvt_pk_bf16_f32 v8, v12, v13
	v_cvt_pk_bf16_f32 v9, v14, v15
	v_cvt_pk_bf16_f32 v10, v20, v21
	v_cvt_pk_bf16_f32 v11, v18, v19
	v_lshl_add_u64 v[22:23], v[22:23], 0, v[166:167]
	global_store_dwordx4 v[22:23], v[8:11], off
	s_nop 0
	v_pk_add_f32 v[6:7], v[6:7], v[98:99]
	v_pk_add_f32 v[4:5], v[4:5], v[96:97]
	v_ashrrev_i32_e32 v8, 11, v16
	v_and_b32_e32 v17, -4, v8
	v_add_u32_e32 v8, v163, v17
	v_ashrrev_i32_e32 v9, 31, v8
	v_lshlrev_b32_e32 v10, 2, v16
	v_lshlrev_b64 v[8:9], 15, v[8:9]
	v_and_b32_e32 v24, 0x7f00, v10
	v_or3_b32 v8, v8, v24, v165
	v_lshlrev_b64 v[8:9], 7, v[8:9]
	v_and_b32_e32 v10, 63, v16
	v_lshl_add_u64 v[8:9], s[92:93], 0, v[8:9]
	v_lshlrev_b32_e32 v152, 1, v10
	v_lshl_add_u64 v[8:9], v[8:9], 0, v[152:153]
	v_lshl_add_u64 v[224:225], v[8:9], 0, v[252:253]
	s_nop 0
	v_mov_b32_dpp v245, v12 quad_perm:[1,0,3,2] row_mask:0xf bank_mask:0xf
	v_mov_b32_dpp v246, v13 quad_perm:[1,0,3,2] row_mask:0xf bank_mask:0xf
	v_cndmask_b32_e64 v247, v12, v246, s[96:97]
	v_cndmask_b32_e64 v248, v245, v13, s[96:97]
	v_cvt_pk_bf16_f32 v247, v247, v248
	global_store_dword v[224:225], v247, off
	v_lshl_add_u64 v[224:225], v[224:225], 0, s[98:99]
	v_mov_b32_dpp v245, v14 quad_perm:[1,0,3,2] row_mask:0xf bank_mask:0xf
	v_mov_b32_dpp v246, v15 quad_perm:[1,0,3,2] row_mask:0xf bank_mask:0xf
	v_cndmask_b32_e64 v247, v14, v246, s[96:97]
	v_cndmask_b32_e64 v248, v245, v15, s[96:97]
	v_cvt_pk_bf16_f32 v247, v247, v248
	global_store_dword v[224:225], v247, off
	v_lshl_add_u64 v[224:225], v[224:225], 0, s[98:99]
	v_mov_b32_dpp v245, v20 quad_perm:[1,0,3,2] row_mask:0xf bank_mask:0xf
	v_mov_b32_dpp v246, v21 quad_perm:[1,0,3,2] row_mask:0xf bank_mask:0xf
	v_cndmask_b32_e64 v247, v20, v246, s[96:97]
	v_cndmask_b32_e64 v248, v245, v21, s[96:97]
	v_cvt_pk_bf16_f32 v247, v247, v248
	global_store_dword v[224:225], v247, off
	v_lshl_add_u64 v[224:225], v[224:225], 0, s[98:99]
	v_mov_b32_dpp v245, v18 quad_perm:[1,0,3,2] row_mask:0xf bank_mask:0xf
	v_mov_b32_dpp v246, v19 quad_perm:[1,0,3,2] row_mask:0xf bank_mask:0xf
	v_cndmask_b32_e64 v247, v18, v246, s[96:97]
	v_cndmask_b32_e64 v248, v245, v19, s[96:97]
	v_cvt_pk_bf16_f32 v247, v247, v248
	global_store_dword v[224:225], v247, off
	v_pk_add_f32 v[10:11], v[0:1], v[92:93]
	v_pk_add_f32 v[8:9], v[2:3], v[94:95]
	v_cvt_pk_bf16_f32 v0, v4, v5
	v_cvt_pk_bf16_f32 v1, v6, v7
	v_cvt_pk_bf16_f32 v2, v10, v11
	v_cvt_pk_bf16_f32 v3, v8, v9
	global_store_dwordx4 v[22:23], v[0:3], off offset:256
	s_nop 0
	s_nop 1
	v_add_u32_e32 v0, v128, v17
	v_ashrrev_i32_e32 v1, 31, v0
	v_lshlrev_b64 v[0:1], 15, v[0:1]
	v_or3_b32 v0, v0, v24, v129
	v_lshlrev_b64 v[0:1], 7, v[0:1]
	v_lshl_add_u64 v[0:1], s[92:93], 0, v[0:1]
	v_lshl_add_u64 v[0:1], v[0:1], 0, v[152:153]
	v_lshl_add_u64 v[224:225], v[0:1], 0, v[252:253]
	s_nop 0
	v_mov_b32_dpp v245, v4 quad_perm:[1,0,3,2] row_mask:0xf bank_mask:0xf
	v_mov_b32_dpp v246, v5 quad_perm:[1,0,3,2] row_mask:0xf bank_mask:0xf
	v_cndmask_b32_e64 v247, v4, v246, s[96:97]
	v_cndmask_b32_e64 v248, v245, v5, s[96:97]
	v_cvt_pk_bf16_f32 v247, v247, v248
	global_store_dword v[224:225], v247, off
	v_lshl_add_u64 v[224:225], v[224:225], 0, s[98:99]
	v_mov_b32_dpp v245, v6 quad_perm:[1,0,3,2] row_mask:0xf bank_mask:0xf
	v_mov_b32_dpp v246, v7 quad_perm:[1,0,3,2] row_mask:0xf bank_mask:0xf
	v_cndmask_b32_e64 v247, v6, v246, s[96:97]
	v_cndmask_b32_e64 v248, v245, v7, s[96:97]
	v_cvt_pk_bf16_f32 v247, v247, v248
	global_store_dword v[224:225], v247, off
	v_lshl_add_u64 v[224:225], v[224:225], 0, s[98:99]
	v_mov_b32_dpp v245, v10 quad_perm:[1,0,3,2] row_mask:0xf bank_mask:0xf
	v_mov_b32_dpp v246, v11 quad_perm:[1,0,3,2] row_mask:0xf bank_mask:0xf
	v_cndmask_b32_e64 v247, v10, v246, s[96:97]
	v_cndmask_b32_e64 v248, v245, v11, s[96:97]
	v_cvt_pk_bf16_f32 v247, v247, v248
	global_store_dword v[224:225], v247, off
	v_lshl_add_u64 v[224:225], v[224:225], 0, s[98:99]
	v_mov_b32_dpp v245, v8 quad_perm:[1,0,3,2] row_mask:0xf bank_mask:0xf
	v_mov_b32_dpp v246, v9 quad_perm:[1,0,3,2] row_mask:0xf bank_mask:0xf
	v_cndmask_b32_e64 v247, v8, v246, s[96:97]
	v_cndmask_b32_e64 v248, v245, v9, s[96:97]
	v_cvt_pk_bf16_f32 v247, v247, v248
	global_store_dword v[224:225], v247, off
	s_andn2_b64 vcc, exec, s[0:1]
	s_mov_b64 s[0:1], -1
	s_cbranch_vccnz .LBB0_279
